# HGRN pass-3 chunk loop: score-chain and state-update LDS reads issued ahead with counted waits (plus earlier MLA/HGRN edits)
# speedup vs baseline: 1.0425x; 1.0057x over previous
; template <int PASS>
; DEV void hgrn_task(unsigned char* lds, int task, int l, const bf16_t* BZ, float* E, float* Dd, float* OF, bf16_t* YB, const float* b_lb, const float* gout) {
;     ...
;                 for (int j = 0; j < 4; ++j) {
;                     const bf16_t* QDj = QD + j * 16 * QP; const bf16_t* KIj = KI + j * 16 * QP; const bf16_t* KETj = KET + j * 128 * 16; const bf16_t* VTj = VT + j * 64 * 16; const float* DECj = DEC + j * 128;
;                     const s16x4 vf = *(const s16x4*)(VTj + (16 * nt + fr) * 16 + 4 * fq);
;                     if (PASS == 3) {
;                         bf16x8 qd[4]; f32x4 sc = {0.f, 0.f, 0.f, 0.f};
; #pragma unroll
;                         for (int kk = 0; kk < 4; ++kk) { const s16x4 a0 = *(const s16x4*)(QDj + fr * QP + 32 * kk + 4 * fq), a1 = *(const s16x4*)(QDj + fr * QP + 32 * kk + 16 + 4 * fq);
;                             qd[kk] = (bf16x8){a0[0], a0[1], a0[2], a0[3], a1[0], a1[1], a1[2], a1[3]};
;                             const s16x4 b0 = *(const s16x4*)(KIj + fr * QP + 32 * kk + 4 * fq), b1 = *(const s16x4*)(KIj + fr * QP + 32 * kk + 16 + 4 * fq);
;                             const bf16x8 kf = {b0[0], b0[1], b0[2], b0[3], b1[0], b1[1], b1[2], b1[3]};
;                             sc = __builtin_amdgcn_mfma_f32_16x16x32_bf16(kf, qd[kk], sc, 0, 0, 0); asm volatile("" :: "v"(kf), "v"(qd[kk])); }
; #pragma unroll
;                         for (int i = 0; i < 4; ++i) if (4 * fq + i > fr) sc[i] = 0.f;
;                         u32x2 sw; sw.x = pk2b(sc[0], sc[1]); sw.y = pk2b(sc[2], sc[3]);
;                         const s16x4 swv = __builtin_bit_cast(s16x4, sw);
;                         f32x4 z4 = {0.f, 0.f, 0.f, 0.f}; asm volatile("" : "+v"(z4));
;                         const bf16x8 sw8 = {swv[0], swv[1], swv[2], swv[3], 0, 0, 0, 0}; const bf16x8 vf8 = {vf[0], vf[1], vf[2], vf[3], 0, 0, 0, 0};
;                         f32x4 oacc = __builtin_amdgcn_mfma_f32_16x16x32_bf16(sw8, vf8, z4, 0, 0, 0); asm volatile("" :: "v"(swv), "v"(vf));
; #pragma unroll
;                         for (int kk = 0; kk < 4; ++kk) { u32x4 sb; sb.x = pk2b(st[2 * kk][0], st[2 * kk][1]); sb.y = pk2b(st[2 * kk][2], st[2 * kk][3]); sb.z = pk2b(st[2 * kk + 1][0], st[2 * kk + 1][1]); sb.w = pk2b(st[2 * kk + 1][2], st[2 * kk + 1][3]);
.LBB0_574:
	v_add_u32_e32 v40, 0, v42
	v_add_u32_e32 v41, 0x4000, v40
	v_add_u32_e32 v38, 0, v43
	ds_read_b64 v[38:39], v38
	ds_read2_b64 v[48:51], v40 offset1:4
	ds_read2_b64 v[134:137], v41 offset0:128 offset1:132
	ds_read2_b64 v[114:117], v40 offset0:8 offset1:12
	ds_read2_b64 v[138:141], v41 offset0:136 offset1:140
	ds_read2_b64 v[122:125], v40 offset0:16 offset1:20
	ds_read2_b64 v[130:133], v40 offset0:24 offset1:28
	v_mov_b32_e32 v129, v128
	v_mov_b32_e32 v126, v128
	v_mov_b32_e32 v127, v128
	s_add_i32 s5, s5, -1
	v_add_u32_e32 v43, 0x800, v43
	v_add_u32_e32 v42, 0x1100, v42
	s_waitcnt lgkmcnt(4)
	v_mfma_f32_16x16x32_bf16 v[118:121], v[134:137], v[48:51], 0
	ds_read2_b64 v[134:137], v41 offset0:144 offset1:148
	s_waitcnt lgkmcnt(3)
	v_mfma_f32_16x16x32_bf16 v[118:121], v[138:141], v[114:117], v[118:121]
	ds_read2_b64 v[138:141], v41 offset0:152 offset1:156
	s_cmp_lg_u32 s5, 0
	s_waitcnt lgkmcnt(1)
	v_mfma_f32_16x16x32_bf16 v[118:121], v[134:137], v[122:125], v[118:121]
	v_mov_b32_e32 v40, s67
	s_waitcnt lgkmcnt(0)
	v_mfma_f32_16x16x32_bf16 v[118:121], v[138:141], v[130:133], v[118:121]
	v_mov_b64_e32 v[136:137], v[128:129]
	v_mov_b64_e32 v[134:135], v[126:127]
	s_nop 5
	v_cndmask_b32_e64 v40, v118, v40, s[8:9]
	v_cndmask_b32_e64 v40, v40, v118, s[10:11]
	v_cndmask_b32_e64 v41, 0, v119, s[10:11]
	v_cndmask_b32_e64 v47, v120, 0, s[12:13]
	v_cndmask_b32_e64 v52, v121, 0, s[14:15]
	v_cvt_pk_bf16_f32 v118, v40, v41
	v_cvt_pk_bf16_f32 v119, v47, v52
	v_mov_b32_e32 v120, v128
	v_mov_b32_e32 v121, v128
	v_mov_b32_e32 v40, v128
	v_mov_b32_e32 v41, v128
	ds_read_b128 v[138:141], v46
	s_nop 0
	v_mfma_f32_16x16x32_bf16 v[134:137], v[118:121], v[38:41], v[134:137]
	v_cvt_pk_bf16_f32 v118, v2, v3
	v_cvt_pk_bf16_f32 v119, v4, v5
	v_cvt_pk_bf16_f32 v120, v6, v7
	v_cvt_pk_bf16_f32 v121, v8, v9
	s_nop 1
	v_mfma_f32_16x16x32_bf16 v[134:137], v[48:51], v[118:121], v[134:137]
	v_cvt_pk_bf16_f32 v48, v10, v11
	v_cvt_pk_bf16_f32 v49, v12, v13
	v_cvt_pk_bf16_f32 v50, v14, v15
	v_cvt_pk_bf16_f32 v51, v16, v17
	s_nop 1
	v_mfma_f32_16x16x32_bf16 v[118:121], v[114:117], v[48:51], v[134:137]
	v_cvt_pk_bf16_f32 v48, v18, v19
	v_cvt_pk_bf16_f32 v49, v20, v21
	v_cvt_pk_bf16_f32 v50, v22, v23
	v_cvt_pk_bf16_f32 v51, v24, v25
	s_nop 1
	v_mfma_f32_16x16x32_bf16 v[114:117], v[122:125], v[48:51], v[118:121]
	ds_read2st64_b64 v[134:137], v45 offset1:1
	v_cvt_pk_bf16_f32 v48, v26, v27
	v_cvt_pk_bf16_f32 v49, v28, v29
	v_cvt_pk_bf16_f32 v50, v30, v31
	v_cvt_pk_bf16_f32 v51, v32, v33
	s_nop 1
	v_mfma_f32_16x16x32_bf16 v[114:117], v[130:133], v[48:51], v[114:117]
	ds_read2st64_b64 v[118:121], v45 offset0:2 offset1:3
	ds_read2st64_b64 v[122:125], v45 offset0:4 offset1:5
	ds_read2st64_b64 v[130:133], v45 offset0:6 offset1:7
	ds_read_b128 v[48:51], v46 offset:64
	s_nop 3
	ds_write_b32 v44, v114 offset:61440
	ds_write_b32 v44, v115 offset:61696
	ds_write_b32 v44, v116 offset:61952
	ds_write_b32 v44, v117 offset:62208
	ds_read_b128 v[114:117], v46 offset:128
	s_waitcnt lgkmcnt(9)
	v_mov_b32_e32 v126, v134
	v_mov_b32_e32 v127, v135
	v_pk_mul_f32 v[4:5], v[4:5], v[140:141]
	v_pk_mul_f32 v[2:3], v[2:3], v[138:139]
	ds_read_b128 v[138:141], v46 offset:192
	s_nop 0
	v_mfma_f32_16x16x32_bf16 v[2:5], v[126:129], v[38:41], v[2:5]
	s_waitcnt lgkmcnt(6)
	v_mov_b32_e32 v126, v136
	v_mov_b32_e32 v127, v137
	v_pk_mul_f32 v[8:9], v[8:9], v[50:51]
	v_pk_mul_f32 v[6:7], v[6:7], v[48:49]
	ds_read_b128 v[48:51], v46 offset:256
	s_nop 0
	v_mfma_f32_16x16x32_bf16 v[6:9], v[126:129], v[38:41], v[6:9]
	s_waitcnt lgkmcnt(2)
	v_mov_b32_e32 v126, v118
	v_mov_b32_e32 v127, v119
	v_pk_mul_f32 v[12:13], v[12:13], v[116:117]
	v_pk_mul_f32 v[10:11], v[10:11], v[114:115]
	ds_read_b128 v[114:117], v46 offset:320
	s_nop 0
	v_mfma_f32_16x16x32_bf16 v[10:13], v[126:129], v[38:41], v[10:13]
	s_waitcnt lgkmcnt(2)
	v_mov_b32_e32 v126, v120
	v_mov_b32_e32 v127, v121
	v_pk_mul_f32 v[16:17], v[16:17], v[140:141]
	v_pk_mul_f32 v[14:15], v[14:15], v[138:139]
	ds_read_b128 v[138:141], v46 offset:384
	s_nop 0
	v_mfma_f32_16x16x32_bf16 v[14:17], v[126:129], v[38:41], v[14:17]
	s_waitcnt lgkmcnt(2)
	v_mov_b32_e32 v126, v122
	v_mov_b32_e32 v127, v123
	v_pk_mul_f32 v[20:21], v[20:21], v[50:51]
	v_pk_mul_f32 v[18:19], v[18:19], v[48:49]
	ds_read_b128 v[48:51], v46 offset:448
	s_nop 0
	v_mfma_f32_16x16x32_bf16 v[18:21], v[126:129], v[38:41], v[18:21]
	s_waitcnt lgkmcnt(2)
	v_mov_b32_e32 v126, v124
	v_mov_b32_e32 v127, v125
	v_pk_mul_f32 v[24:25], v[24:25], v[116:117]
	v_pk_mul_f32 v[22:23], v[22:23], v[114:115]
	s_nop 1
	v_mfma_f32_16x16x32_bf16 v[22:25], v[126:129], v[38:41], v[22:25]
	s_waitcnt lgkmcnt(1)
	v_mov_b32_e32 v126, v130
	v_mov_b32_e32 v127, v131
	v_pk_mul_f32 v[28:29], v[28:29], v[140:141]
	v_pk_mul_f32 v[26:27], v[26:27], v[138:139]
	s_nop 1
	v_mfma_f32_16x16x32_bf16 v[26:29], v[126:129], v[38:41], v[26:29]
	s_waitcnt lgkmcnt(0)
	v_mov_b32_e32 v126, v132
	v_mov_b32_e32 v127, v133
	v_pk_mul_f32 v[32:33], v[32:33], v[50:51]
	v_pk_mul_f32 v[30:31], v[30:31], v[48:49]
	s_nop 1
	v_mfma_f32_16x16x32_bf16 v[30:33], v[126:129], v[38:41], v[30:33]
	v_add_u32_e32 v44, 0x1000, v44
	v_add_u32_e32 v45, 0x1000, v45
	v_add_u32_e32 v46, 0x200, v46
	s_cbranch_scc1 .LBB0_574
